# GEMM accumulator clears use 64-bit moves (half the VALU instructions per tile)
# baseline (speedup 1.0000x reference)
; template <class Epi, class Sched, bool ALIGN_EPI = false, bool SP2 = false>
; __device__ __forceinline__ void gemm_phase(PG8_LAS unsigned char* lds, const Gemm g, const Sched& S, const Epi& E) {
;     ...
;         const bool has_next = S.next(ui + 1, nxt);
;         const char* nA = has_next ? (const char*)g.A + (size_t)nxt.pm * tstep : cA; const char* nB = has_next ? (const char*)g.Bt + (size_t)nxt.pn * tstep : cB;
;     ...
;         for (int a = 0; a < 2; ++a)
; #pragma unroll
;             for (int b = 0; b < 2; ++b)
; #pragma unroll
;                 for (int m = 0; m < 4; ++m)
; #pragma unroll
;                     for (int n = 0; n < 2; ++n) acc[a][b][m][n] = (f32x4){0.f, 0.f, 0.f, 0.f};
.LBB0_170:
	s_ashr_i32 s29, s28, 31
	s_lshl_b64 s[30:31], s[28:29], 20
	s_add_u32 s30, s13, s30
	s_addc_u32 s31, s47, s31
	s_and_b64 s[34:35], s[38:39], exec
	s_cselect_b32 s29, s31, s41
	s_cselect_b32 s37, s30, s40
	s_ashr_i32 s27, s26, 31
	s_lshl_b64 s[34:35], s[26:27], 20
	s_add_u32 s34, s48, s34
	s_addc_u32 s35, s49, s35
	s_and_b64 s[44:45], s[38:39], exec
	s_cselect_b32 s27, s35, s43
	s_cselect_b32 s65, s34, s42
	s_add_u32 s40, s40, 0x80080
	s_addc_u32 s41, s41, 0
	s_add_u32 s67, s42, 0x100
	s_addc_u32 s68, s43, 0
	s_mov_b32 s69, -2
	v_mov_b64_e32 v[0:1], 0
	v_mov_b64_e32 v[2:3], 0
	v_mov_b64_e32 v[4:5], 0
	v_mov_b64_e32 v[6:7], 0
	v_mov_b64_e32 v[8:9], 0
	v_mov_b64_e32 v[10:11], 0
	v_mov_b64_e32 v[12:13], 0
	v_mov_b64_e32 v[14:15], 0
	v_mov_b64_e32 v[16:17], 0
	v_mov_b64_e32 v[18:19], 0
	v_mov_b64_e32 v[20:21], 0
	v_mov_b64_e32 v[22:23], 0
	v_mov_b64_e32 v[24:25], 0
	v_mov_b64_e32 v[26:27], 0
	v_mov_b64_e32 v[28:29], 0
	v_mov_b64_e32 v[30:31], 0
	v_mov_b64_e32 v[32:33], 0
	v_mov_b64_e32 v[34:35], 0
	v_mov_b64_e32 v[36:37], 0
	v_mov_b64_e32 v[38:39], 0
	v_mov_b64_e32 v[40:41], 0
	v_mov_b64_e32 v[42:43], 0
	v_mov_b64_e32 v[44:45], 0
	v_mov_b64_e32 v[46:47], 0
	v_mov_b64_e32 v[48:49], 0
	v_mov_b64_e32 v[50:51], 0
	v_mov_b64_e32 v[52:53], 0
	v_mov_b64_e32 v[54:55], 0
	v_mov_b64_e32 v[56:57], 0
	v_mov_b64_e32 v[58:59], 0
	v_mov_b64_e32 v[60:61], 0
	v_mov_b64_e32 v[62:63], 0
	v_mov_b64_e32 v[64:65], 0
	v_mov_b64_e32 v[66:67], 0
	v_mov_b64_e32 v[68:69], 0
	v_mov_b64_e32 v[70:71], 0
	v_mov_b64_e32 v[72:73], 0
	v_mov_b64_e32 v[74:75], 0
	v_mov_b64_e32 v[76:77], 0
	v_mov_b64_e32 v[78:79], 0
	v_mov_b64_e32 v[80:81], 0
	v_mov_b64_e32 v[82:83], 0
	v_mov_b64_e32 v[84:85], 0
	v_mov_b64_e32 v[86:87], 0
	v_mov_b64_e32 v[88:89], 0
	v_mov_b64_e32 v[90:91], 0
	v_mov_b64_e32 v[92:93], 0
	v_mov_b64_e32 v[94:95], 0
	v_mov_b64_e32 v[96:97], 0
	v_mov_b64_e32 v[98:99], 0
	v_mov_b64_e32 v[100:101], 0
	v_mov_b64_e32 v[102:103], 0
	v_mov_b64_e32 v[104:105], 0
	v_mov_b64_e32 v[106:107], 0
	v_mov_b64_e32 v[108:109], 0
	v_mov_b64_e32 v[110:111], 0
	v_mov_b64_e32 v[112:113], 0
	v_mov_b64_e32 v[114:115], 0
	v_mov_b64_e32 v[116:117], 0
	v_mov_b64_e32 v[118:119], 0
	v_mov_b64_e32 v[120:121], 0
	v_mov_b64_e32 v[122:123], 0
	v_mov_b64_e32 v[124:125], 0
	v_mov_b64_e32 v[126:127], 0

; template <class Epi, class Sched, bool ALIGN_EPI = false, bool SP2 = false>
; __device__ __forceinline__ void gemm_phase(PG8_LAS unsigned char* lds, const Gemm g, const Sched& S, const Epi& E) {
;     ...
;         const bool has_next = S.next(ui + 1, nxt);
;         const char* nA = has_next ? (const char*)g.A + (size_t)nxt.pm * tstep : cA; const char* nB = has_next ? (const char*)g.Bt + (size_t)nxt.pn * tstep : cB;
;     ...
;         for (int a = 0; a < 2; ++a)
; #pragma unroll
;             for (int b = 0; b < 2; ++b)
; #pragma unroll
;                 for (int m = 0; m < 4; ++m)
; #pragma unroll
;                     for (int n = 0; n < 2; ++n) acc[a][b][m][n] = (f32x4){0.f, 0.f, 0.f, 0.f};
.LBB0_552:
	s_ashr_i32 s35, s34, 31
	s_lshl_b64 s[36:37], s[34:35], 19
	s_add_u32 s36, s13, s36
	s_addc_u32 s37, s47, s37
	s_and_b64 s[40:41], s[38:39], exec
	s_cselect_b32 s35, s37, s51
	s_cselect_b32 s72, s36, s50
	s_ashr_i32 s31, s30, 31
	s_lshl_b64 s[40:41], s[30:31], 19
	s_add_u32 s40, s60, s40
	s_addc_u32 s41, s61, s41
	s_and_b64 s[54:55], s[38:39], exec
	s_cselect_b32 s31, s41, s53
	s_cselect_b32 s73, s40, s52
	s_add_u32 s50, s50, 0x40080
	s_addc_u32 s51, s51, 0
	s_add_u32 s74, s52, 0x100
	s_addc_u32 s75, s53, 0
	s_mov_b32 s76, -2
	s_waitcnt vmcnt(0)
	v_mov_b64_e32 v[0:1], 0
	v_mov_b64_e32 v[2:3], 0
	v_mov_b64_e32 v[4:5], 0
	v_mov_b64_e32 v[6:7], 0
	v_mov_b64_e32 v[8:9], 0
	v_mov_b64_e32 v[10:11], 0
	v_mov_b64_e32 v[12:13], 0
	v_mov_b64_e32 v[14:15], 0
	v_mov_b64_e32 v[16:17], 0
	v_mov_b64_e32 v[18:19], 0
	v_mov_b64_e32 v[20:21], 0
	v_mov_b64_e32 v[22:23], 0
	v_mov_b64_e32 v[24:25], 0
	v_mov_b64_e32 v[26:27], 0
	v_mov_b64_e32 v[28:29], 0
	v_mov_b64_e32 v[30:31], 0
	v_mov_b64_e32 v[32:33], 0
	v_mov_b64_e32 v[34:35], 0
	v_mov_b64_e32 v[36:37], 0
	v_mov_b64_e32 v[38:39], 0
	v_mov_b64_e32 v[40:41], 0
	v_mov_b64_e32 v[42:43], 0
	v_mov_b64_e32 v[44:45], 0
	v_mov_b64_e32 v[46:47], 0
	v_mov_b64_e32 v[48:49], 0
	v_mov_b64_e32 v[50:51], 0
	v_mov_b64_e32 v[52:53], 0
	v_mov_b64_e32 v[54:55], 0
	v_mov_b64_e32 v[56:57], 0
	v_mov_b64_e32 v[58:59], 0
	v_mov_b64_e32 v[60:61], 0
	v_mov_b64_e32 v[62:63], 0
	v_mov_b64_e32 v[64:65], 0
	v_mov_b64_e32 v[66:67], 0
	v_mov_b64_e32 v[68:69], 0
	v_mov_b64_e32 v[70:71], 0
	v_mov_b64_e32 v[72:73], 0
	v_mov_b64_e32 v[74:75], 0
	v_mov_b64_e32 v[76:77], 0
	v_mov_b64_e32 v[78:79], 0
	v_mov_b64_e32 v[80:81], 0
	v_mov_b64_e32 v[82:83], 0
	v_mov_b64_e32 v[84:85], 0
	v_mov_b64_e32 v[86:87], 0
	v_mov_b64_e32 v[88:89], 0
	v_mov_b64_e32 v[90:91], 0
	v_mov_b64_e32 v[92:93], 0
	v_mov_b64_e32 v[94:95], 0
	v_mov_b64_e32 v[96:97], 0
	v_mov_b64_e32 v[98:99], 0
	v_mov_b64_e32 v[100:101], 0
	v_mov_b64_e32 v[102:103], 0
	v_mov_b64_e32 v[104:105], 0
	v_mov_b64_e32 v[106:107], 0
	v_mov_b64_e32 v[108:109], 0
	v_mov_b64_e32 v[110:111], 0
	v_mov_b64_e32 v[112:113], 0
	v_mov_b64_e32 v[114:115], 0
	v_mov_b64_e32 v[116:117], 0
	v_mov_b64_e32 v[118:119], 0
	v_mov_b64_e32 v[120:121], 0
	v_mov_b64_e32 v[122:123], 0
	v_mov_b64_e32 v[124:125], 0
	v_mov_b64_e32 v[126:127], 0

; template <class Epi, class Sched, bool ALIGN_EPI = false, bool SP2 = false>
; __device__ __forceinline__ void gemm_phase(PG8_LAS unsigned char* lds, const Gemm g, const Sched& S, const Epi& E) {
;     ...
;         const bool has_next = S.next(ui + 1, nxt);
;         const char* nA = has_next ? (const char*)g.A + (size_t)nxt.pm * tstep : cA; const char* nB = has_next ? (const char*)g.Bt + (size_t)nxt.pn * tstep : cB;
;     ...
;         for (int a = 0; a < 2; ++a)
; #pragma unroll
;             for (int b = 0; b < 2; ++b)
; #pragma unroll
;                 for (int m = 0; m < 4; ++m)
; #pragma unroll
;                     for (int n = 0; n < 2; ++n) acc[a][b][m][n] = (f32x4){0.f, 0.f, 0.f, 0.f};
.LBB0_572:
	s_ashr_i32 s27, s26, 31
	s_lshl_b64 s[28:29], s[26:27], 19
	s_add_u32 s28, s47, s28
	s_addc_u32 s29, s52, s29
	s_and_b64 s[30:31], s[40:41], exec
	s_cselect_b32 s27, s29, s37
	s_cselect_b32 s68, s28, s36
	s_ashr_i32 s25, s24, 31
	s_lshl_b64 s[30:31], s[24:25], 19
	s_add_u32 s30, s53, s30
	s_addc_u32 s31, s54, s31
	s_and_b64 s[50:51], s[40:41], exec
	s_cselect_b32 s25, s31, s45
	s_cselect_b32 s69, s30, s44
	s_add_u32 s36, s36, 0x40080
	s_addc_u32 s37, s37, 0
	s_add_u32 s70, s44, 0x100
	s_addc_u32 s71, s45, 0
	s_mov_b32 s72, -2
	v_mov_b64_e32 v[0:1], 0
	v_mov_b64_e32 v[2:3], 0
	v_mov_b64_e32 v[4:5], 0
	v_mov_b64_e32 v[6:7], 0
	v_mov_b64_e32 v[8:9], 0
	v_mov_b64_e32 v[10:11], 0
	v_mov_b64_e32 v[12:13], 0
	v_mov_b64_e32 v[14:15], 0
	v_mov_b64_e32 v[16:17], 0
	v_mov_b64_e32 v[18:19], 0
	v_mov_b64_e32 v[20:21], 0
	v_mov_b64_e32 v[22:23], 0
	v_mov_b64_e32 v[24:25], 0
	v_mov_b64_e32 v[26:27], 0
	v_mov_b64_e32 v[28:29], 0
	v_mov_b64_e32 v[30:31], 0
	v_mov_b64_e32 v[32:33], 0
	v_mov_b64_e32 v[34:35], 0
	v_mov_b64_e32 v[36:37], 0
	v_mov_b64_e32 v[38:39], 0
	v_mov_b64_e32 v[40:41], 0
	v_mov_b64_e32 v[42:43], 0
	v_mov_b64_e32 v[44:45], 0
	v_mov_b64_e32 v[46:47], 0
	v_mov_b64_e32 v[48:49], 0
	v_mov_b64_e32 v[50:51], 0
	v_mov_b64_e32 v[52:53], 0
	v_mov_b64_e32 v[54:55], 0
	v_mov_b64_e32 v[56:57], 0
	v_mov_b64_e32 v[58:59], 0
	v_mov_b64_e32 v[60:61], 0
	v_mov_b64_e32 v[62:63], 0
	v_mov_b64_e32 v[64:65], 0
	v_mov_b64_e32 v[66:67], 0
	v_mov_b64_e32 v[68:69], 0
	v_mov_b64_e32 v[70:71], 0
	v_mov_b64_e32 v[72:73], 0
	v_mov_b64_e32 v[74:75], 0
	v_mov_b64_e32 v[76:77], 0
	v_mov_b64_e32 v[78:79], 0
	v_mov_b64_e32 v[80:81], 0
	v_mov_b64_e32 v[82:83], 0
	v_mov_b64_e32 v[84:85], 0
	v_mov_b64_e32 v[86:87], 0
	v_mov_b64_e32 v[88:89], 0
	v_mov_b64_e32 v[90:91], 0
	v_mov_b64_e32 v[92:93], 0
	v_mov_b64_e32 v[94:95], 0
	v_mov_b64_e32 v[96:97], 0
	v_mov_b64_e32 v[98:99], 0
	v_mov_b64_e32 v[100:101], 0
	v_mov_b64_e32 v[102:103], 0
	v_mov_b64_e32 v[104:105], 0
	v_mov_b64_e32 v[106:107], 0
	v_mov_b64_e32 v[108:109], 0
	v_mov_b64_e32 v[110:111], 0
	v_mov_b64_e32 v[112:113], 0
	v_mov_b64_e32 v[114:115], 0
	v_mov_b64_e32 v[116:117], 0
	v_mov_b64_e32 v[118:119], 0
	v_mov_b64_e32 v[120:121], 0
	v_mov_b64_e32 v[122:123], 0
	v_mov_b64_e32 v[124:125], 0
	v_mov_b64_e32 v[126:127], 0

; template <class Epi, class Sched, bool ALIGN_EPI = false, bool SP2 = false>
; __device__ __forceinline__ void gemm_phase(PG8_LAS unsigned char* lds, const Gemm g, const Sched& S, const Epi& E) {
;     ...
;         const bool has_next = S.next(ui + 1, nxt);
;         const char* nA = has_next ? (const char*)g.A + (size_t)nxt.pm * tstep : cA; const char* nB = has_next ? (const char*)g.Bt + (size_t)nxt.pn * tstep : cB;
;     ...
;         for (int a = 0; a < 2; ++a)
; #pragma unroll
;             for (int b = 0; b < 2; ++b)
; #pragma unroll
;                 for (int m = 0; m < 4; ++m)
; #pragma unroll
;                     for (int n = 0; n < 2; ++n) acc[a][b][m][n] = (f32x4){0.f, 0.f, 0.f, 0.f};
.LBB0_644:
	s_ashr_i32 s27, s26, 31
	s_lshl_b64 s[28:29], s[26:27], 20
	s_add_u32 s28, s13, s28
	s_addc_u32 s29, s47, s29
	s_and_b64 s[30:31], s[38:39], exec
	s_cselect_b32 s27, s29, s37
	s_cselect_b32 s70, s28, s36
	s_ashr_i32 s25, s24, 31
	s_lshl_b64 s[30:31], s[24:25], 20
	s_add_u32 s30, s52, s30
	s_addc_u32 s31, s53, s31
	s_and_b64 s[44:45], s[38:39], exec
	s_cselect_b32 s25, s31, s41
	s_cselect_b32 s71, s30, s40
	s_add_u32 s72, s40, 0x100
	s_addc_u32 s73, s41, 0
	s_mov_b32 s74, -2
	v_mov_b64_e32 v[0:1], 0
	v_mov_b64_e32 v[2:3], 0
	v_mov_b64_e32 v[4:5], 0
	v_mov_b64_e32 v[6:7], 0
	v_mov_b64_e32 v[8:9], 0
	v_mov_b64_e32 v[10:11], 0
	v_mov_b64_e32 v[12:13], 0
	v_mov_b64_e32 v[14:15], 0
	v_mov_b64_e32 v[16:17], 0
	v_mov_b64_e32 v[18:19], 0
	v_mov_b64_e32 v[20:21], 0
	v_mov_b64_e32 v[22:23], 0
	v_mov_b64_e32 v[24:25], 0
	v_mov_b64_e32 v[26:27], 0
	v_mov_b64_e32 v[28:29], 0
	v_mov_b64_e32 v[30:31], 0
	v_mov_b64_e32 v[32:33], 0
	v_mov_b64_e32 v[34:35], 0
	v_mov_b64_e32 v[36:37], 0
	v_mov_b64_e32 v[38:39], 0
	v_mov_b64_e32 v[40:41], 0
	v_mov_b64_e32 v[42:43], 0
	v_mov_b64_e32 v[44:45], 0
	v_mov_b64_e32 v[46:47], 0
	v_mov_b64_e32 v[48:49], 0
	v_mov_b64_e32 v[50:51], 0
	v_mov_b64_e32 v[52:53], 0
	v_mov_b64_e32 v[54:55], 0
	v_mov_b64_e32 v[56:57], 0
	v_mov_b64_e32 v[58:59], 0
	v_mov_b64_e32 v[60:61], 0
	v_mov_b64_e32 v[62:63], 0
	v_mov_b64_e32 v[64:65], 0
	v_mov_b64_e32 v[66:67], 0
	v_mov_b64_e32 v[68:69], 0
	v_mov_b64_e32 v[70:71], 0
	v_mov_b64_e32 v[72:73], 0
	v_mov_b64_e32 v[74:75], 0
	v_mov_b64_e32 v[76:77], 0
	v_mov_b64_e32 v[78:79], 0
	v_mov_b64_e32 v[80:81], 0
	v_mov_b64_e32 v[82:83], 0
	v_mov_b64_e32 v[84:85], 0
	v_mov_b64_e32 v[86:87], 0
	v_mov_b64_e32 v[88:89], 0
	v_mov_b64_e32 v[90:91], 0
	v_mov_b64_e32 v[96:97], 0
	v_mov_b64_e32 v[98:99], 0
	v_mov_b64_e32 v[104:105], 0
	v_mov_b64_e32 v[106:107], 0
	v_mov_b64_e32 v[112:113], 0
	v_mov_b64_e32 v[114:115], 0
	v_mov_b64_e32 v[120:121], 0
	v_mov_b64_e32 v[122:123], 0
	v_mov_b64_e32 v[124:125], 0
	v_mov_b64_e32 v[126:127], 0
	v_mov_b64_e32 v[128:129], 0
	v_mov_b64_e32 v[130:131], 0
	v_mov_b64_e32 v[132:133], 0
	v_mov_b64_e32 v[134:135], 0
	v_mov_b64_e32 v[136:137], 0
	v_mov_b64_e32 v[138:139], 0
	v_mov_b64_e32 v[140:141], 0
	v_mov_b64_e32 v[142:143], 0

; template <class Epi, class Sched, bool ALIGN_EPI = false, bool SP2 = false>
; __device__ __forceinline__ void gemm_phase(PG8_LAS unsigned char* lds, const Gemm g, const Sched& S, const Epi& E) {
;     ...
;         const bool has_next = S.next(ui + 1, nxt);
;         const char* nA = has_next ? (const char*)g.A + (size_t)nxt.pm * tstep : cA; const char* nB = has_next ? (const char*)g.Bt + (size_t)nxt.pn * tstep : cB;
;     ...
;         for (int a = 0; a < 2; ++a)
; #pragma unroll
;             for (int b = 0; b < 2; ++b)
; #pragma unroll
;                 for (int m = 0; m < 4; ++m)
; #pragma unroll
;                     for (int n = 0; n < 2; ++n) acc[a][b][m][n] = (f32x4){0.f, 0.f, 0.f, 0.f};
.LBB0_774:
	s_ashr_i32 s23, s22, 31
	s_lshl_b64 s[24:25], s[22:23], 20
	s_add_u32 s24, s40, s24
	s_addc_u32 s25, s41, s25
	s_and_b64 s[26:27], s[38:39], exec
	s_cselect_b32 s23, s25, s31
	s_cselect_b32 s62, s24, s30
	s_ashr_i32 s21, s20, 31
	s_lshl_b64 s[26:27], s[20:21], 20
	s_add_u32 s26, s44, s26
	s_addc_u32 s27, s45, s27
	s_and_b64 s[36:37], s[38:39], exec
	s_cselect_b32 s21, s27, s35
	s_cselect_b32 s63, s26, s34
	s_add_u32 s30, s30, 0x80080
	s_addc_u32 s31, s31, 0
	s_add_u32 s64, s34, 0x100
	s_addc_u32 s65, s35, 0
	s_mov_b32 s66, -2
	v_mov_b64_e32 v[0:1], 0
	v_mov_b64_e32 v[2:3], 0
	v_mov_b64_e32 v[4:5], 0
	v_mov_b64_e32 v[6:7], 0
	v_mov_b64_e32 v[8:9], 0
	v_mov_b64_e32 v[10:11], 0
	v_mov_b64_e32 v[12:13], 0
	v_mov_b64_e32 v[14:15], 0
	v_mov_b64_e32 v[16:17], 0
	v_mov_b64_e32 v[18:19], 0
	v_mov_b64_e32 v[20:21], 0
	v_mov_b64_e32 v[22:23], 0
	v_mov_b64_e32 v[24:25], 0
	v_mov_b64_e32 v[26:27], 0
	v_mov_b64_e32 v[28:29], 0
	v_mov_b64_e32 v[30:31], 0
	v_mov_b64_e32 v[32:33], 0
	v_mov_b64_e32 v[34:35], 0
	v_mov_b64_e32 v[36:37], 0
	v_mov_b64_e32 v[38:39], 0
	v_mov_b64_e32 v[40:41], 0
	v_mov_b64_e32 v[42:43], 0
	v_mov_b64_e32 v[44:45], 0
	v_mov_b64_e32 v[46:47], 0
	v_mov_b64_e32 v[48:49], 0
	v_mov_b64_e32 v[50:51], 0
	v_mov_b64_e32 v[52:53], 0
	v_mov_b64_e32 v[54:55], 0
	v_mov_b64_e32 v[56:57], 0
	v_mov_b64_e32 v[58:59], 0
	v_mov_b64_e32 v[60:61], 0
	v_mov_b64_e32 v[62:63], 0
	v_mov_b64_e32 v[64:65], 0
	v_mov_b64_e32 v[66:67], 0
	v_mov_b64_e32 v[68:69], 0
	v_mov_b64_e32 v[70:71], 0
	v_mov_b64_e32 v[72:73], 0
	v_mov_b64_e32 v[74:75], 0
	v_mov_b64_e32 v[76:77], 0
	v_mov_b64_e32 v[78:79], 0
	v_mov_b64_e32 v[80:81], 0
	v_mov_b64_e32 v[82:83], 0
	v_mov_b64_e32 v[84:85], 0
	v_mov_b64_e32 v[86:87], 0
	v_mov_b64_e32 v[88:89], 0
	v_mov_b64_e32 v[90:91], 0
	v_mov_b64_e32 v[92:93], 0
	v_mov_b64_e32 v[94:95], 0
	v_mov_b64_e32 v[96:97], 0
	v_mov_b64_e32 v[98:99], 0
	v_mov_b64_e32 v[100:101], 0
	v_mov_b64_e32 v[102:103], 0
	v_mov_b64_e32 v[104:105], 0
	v_mov_b64_e32 v[106:107], 0
	v_mov_b64_e32 v[108:109], 0
	v_mov_b64_e32 v[110:111], 0
	v_mov_b64_e32 v[112:113], 0
	v_mov_b64_e32 v[114:115], 0
	v_mov_b64_e32 v[116:117], 0
	v_mov_b64_e32 v[118:119], 0
	v_mov_b64_e32 v[120:121], 0
	v_mov_b64_e32 v[122:123], 0
	v_mov_b64_e32 v[124:125], 0
	v_mov_b64_e32 v[126:127], 0

; template <class Epi, class Sched, bool ALIGN_EPI = false, bool SP2 = false>
; __device__ __forceinline__ void gemm_phase(PG8_LAS unsigned char* lds, const Gemm g, const Sched& S, const Epi& E) {
;     ...
;         const bool has_next = S.next(ui + 1, nxt);
;         const char* nA = has_next ? (const char*)g.A + (size_t)nxt.pm * tstep : cA; const char* nB = has_next ? (const char*)g.Bt + (size_t)nxt.pn * tstep : cB;
;     ...
;         for (int a = 0; a < 2; ++a)
; #pragma unroll
;             for (int b = 0; b < 2; ++b)
; #pragma unroll
;                 for (int m = 0; m < 4; ++m)
; #pragma unroll
;                     for (int n = 0; n < 2; ++n) acc[a][b][m][n] = (f32x4){0.f, 0.f, 0.f, 0.f};
.LBB0_846:
	s_ashr_i32 s23, s22, 31
	s_lshl_b64 s[24:25], s[22:23], 22
	s_add_u32 s24, s40, s24
	s_addc_u32 s25, s41, s25
	s_and_b64 s[26:27], s[0:1], exec
	s_cselect_b32 s23, s25, s31
	s_cselect_b32 s57, s24, s30
	s_ashr_i32 s21, s20, 31
	s_lshl_b64 s[26:27], s[20:21], 22
	s_add_u32 s26, s44, s26
	s_addc_u32 s27, s45, s27
	s_and_b64 s[36:37], s[0:1], exec
	s_cselect_b32 s21, s27, s35
	s_cselect_b32 s58, s26, s34
	s_add_u32 s59, s34, 0x100
	s_addc_u32 s60, s35, 0
	s_mov_b32 s61, -2
	v_mov_b64_e32 v[0:1], 0
	v_mov_b64_e32 v[2:3], 0
	v_mov_b64_e32 v[4:5], 0
	v_mov_b64_e32 v[6:7], 0
	v_mov_b64_e32 v[8:9], 0
	v_mov_b64_e32 v[10:11], 0
	v_mov_b64_e32 v[12:13], 0
	v_mov_b64_e32 v[14:15], 0
	v_mov_b64_e32 v[16:17], 0
	v_mov_b64_e32 v[18:19], 0
	v_mov_b64_e32 v[20:21], 0
	v_mov_b64_e32 v[22:23], 0
	v_mov_b64_e32 v[24:25], 0
	v_mov_b64_e32 v[26:27], 0
	v_mov_b64_e32 v[28:29], 0
	v_mov_b64_e32 v[30:31], 0
	v_mov_b64_e32 v[32:33], 0
	v_mov_b64_e32 v[34:35], 0
	v_mov_b64_e32 v[36:37], 0
	v_mov_b64_e32 v[38:39], 0
	v_mov_b64_e32 v[40:41], 0
	v_mov_b64_e32 v[42:43], 0
	v_mov_b64_e32 v[44:45], 0
	v_mov_b64_e32 v[46:47], 0
	v_mov_b64_e32 v[48:49], 0
	v_mov_b64_e32 v[50:51], 0
	v_mov_b64_e32 v[52:53], 0
	v_mov_b64_e32 v[54:55], 0
	v_mov_b64_e32 v[56:57], 0
	v_mov_b64_e32 v[58:59], 0
	v_mov_b64_e32 v[60:61], 0
	v_mov_b64_e32 v[62:63], 0
	v_mov_b64_e32 v[64:65], 0
	v_mov_b64_e32 v[66:67], 0
	v_mov_b64_e32 v[68:69], 0
	v_mov_b64_e32 v[70:71], 0
	v_mov_b64_e32 v[76:77], 0
	v_mov_b64_e32 v[78:79], 0
	v_mov_b64_e32 v[80:81], 0
	v_mov_b64_e32 v[82:83], 0
	v_mov_b64_e32 v[88:89], 0
	v_mov_b64_e32 v[90:91], 0
	v_mov_b64_e32 v[96:97], 0
	v_mov_b64_e32 v[98:99], 0
	v_mov_b64_e32 v[100:101], 0
	v_mov_b64_e32 v[102:103], 0
	v_mov_b64_e32 v[104:105], 0
	v_mov_b64_e32 v[106:107], 0
	v_mov_b64_e32 v[112:113], 0
	v_mov_b64_e32 v[114:115], 0
	v_mov_b64_e32 v[116:117], 0
	v_mov_b64_e32 v[118:119], 0
	v_mov_b64_e32 v[120:121], 0
	v_mov_b64_e32 v[122:123], 0
	v_mov_b64_e32 v[124:125], 0
	v_mov_b64_e32 v[126:127], 0
	v_mov_b64_e32 v[128:129], 0
	v_mov_b64_e32 v[130:131], 0
	v_mov_b64_e32 v[132:133], 0
	v_mov_b64_e32 v[134:135], 0
	v_mov_b64_e32 v[136:137], 0
	v_mov_b64_e32 v[138:139], 0
	v_mov_b64_e32 v[140:141], 0
	v_mov_b64_e32 v[142:143], 0
